# compress GEMM1 loads software-pipelined; diff-attention interior key tiles skip the hoisted causal-mask compares
# speedup vs baseline: 1.0084x; 1.0084x over previous
; template <bool MASKED>
; __device__ __forceinline__ void sm_step(f32x4 (&S)[4], float c1, float slope2, float tb, int kbase, int tqn,
;                                         int window, bool selok, bf16x8 (&pb)[2]) {
; #pragma unroll
;   for (int mt = 0; mt < 4; ++mt)
; #pragma unroll
;     for (int r = 0; r < 4; ++r) {
;       float u = fmaf(slope2, (float)(mt * 16 + r), fmaf(S[mt][r], c1, tb));
;       if (MASKED) {
;         int dist = tqn - (kbase + mt * 16 + r);
;         bool valid = (dist >= 0) && (dist < window) && selok;
;         u = valid ? u : -1e30f;
;       }
;       S[mt][r] = fexp2(u);
;     }
; #pragma unroll
;     ...
;     for (int hk = 0; hk < TK; ++hk) {
;     const u16* cK = sK + stg * FST + hk * TSZ;
;     const u16* cV = cK + 64 * 72;
;     const int k0 = (kt + hk) * 64;
;     if (k0 <= qhi && (qlo - (k0 + 63)) < window) {
;       bool full = (k0 + 63 <= qlo) && (qhi - k0 < window);
;       const bool rowfull = SEL && full;
;       bool selok[NQ];
; #pragma unroll
;       for (int n = 0; n < NQ; ++n) selok[n] = true;
;       if (SEL) {
;         bool all = true;
; #pragma unroll
;         for (int n = 0; n < NQ; ++n) { selok[n] = ((selq[n] >> kt) & 1u) != 0; all = all && selok[n]; }
;         full = full && __all(all);
;       }
;       const int kbase = k0 + quad * 4;
; #pragma unroll
;       for (int mp = 0; mp < NMAP; ++mp) {
; #pragma unroll
;         for (int n = 0; n < NQ; ++n) {
;           f32x4 S[4];
; #pragma unroll
;           for (int mt = 0; mt < 4; ++mt) S[mt] = f32x4{0.f, 0.f, 0.f, 0.f};
; #pragma unroll
;           for (int ks = 0; ks < 2; ++ks) {
;             if (NMAP == 2 && ks != mp) continue;
; #pragma unroll
;             for (int mt = 0; mt < 4; ++mt) {
;               bf16x8 a = *(const bf16x8*)(cK + (mt * 16 + l15) * 64 + (((ks * 4 + quad) ^ ((l15 >> 1) & 7)) * 8));
;               S[mt] = mfma16(a, qf[n][ks], S[mt]);
;             }
;           }
;           bf16x8 pb[2];
;           const float tb = slope2 * (float)(kbase - tq[n]);
;           if (full || rowfull) {
;             sm_step<false>(S, c1, slope2, tb, kbase, tq[n], window, true, pb);
;             if (SEL && !full && !selok[n]) {
;               pb[0] = bf16x8{0, 0, 0, 0, 0, 0, 0, 0}; pb[1] = bf16x8{0, 0, 0, 0, 0, 0, 0, 0};
;             }
;           } else sm_step<true>(S, c1, slope2, tb, kbase, tq[n], window, selok[n], pb);
.LBB0_209:
	s_mul_i32 s83, s81, 0x9000
	v_add_u32_e32 v0, s83, v148
	s_cmp_gt_i32 s80, s77
	v_add_u32_e32 v156, s80, v153
	v_add_u32_e32 v154, s35, v152
	v_add_u32_e32 v155, v0, v150
	s_cbranch_scc1 .LBB0_219
	s_add_i32 s29, s80, 63
	s_cmp_eq_u32 s35, s79
	s_cselect_b64 s[30:31], -1, 0
	s_cmp_gt_i32 s29, s74
	s_cselect_b64 s[38:39], -1, 0
	s_or_b64 s[72:73], s[38:39], s[30:31]
	s_and_b64 vcc, exec, s[72:73]
	s_cbranch_vccz .Ldiff_t0_fast
	v_add_u32_e32 v2, 0xfffff840, v156
	v_cvt_f32_i32_e32 v3, v2
	v_cmp_lt_u32_e64 s[48:49], s34, v2
	v_add_u32_e32 v2, 0x7be, v154
	v_cmp_gt_u32_e64 s[50:51], s26, v2
	v_add_u32_e32 v2, 0x7bd, v154
	ds_read_b128 v[84:87], v155
	ds_read_b128 v[88:91], v155 offset:2048
	v_cmp_gt_u32_e64 s[52:53], s26, v2
	v_add_u32_e32 v2, 0x7b0, v154
	ds_read_b128 v[92:95], v155 offset:4096
	ds_read_b128 v[96:99], v155 offset:6144
	s_add_i32 s29, s80, 63
	v_cmp_gt_u32_e64 s[46:47], s26, v2
	v_add_u32_e32 v2, 0x7af, v154
	s_cmp_eq_u32 s35, s79
	v_cmp_gt_u32_e64 s[44:45], s26, v2
	v_add_u32_e32 v2, 0x7ae, v154
	s_cselect_b64 s[30:31], -1, 0
	s_cmp_gt_i32 s29, s74
	v_cmp_gt_u32_e64 s[42:43], s26, v2
	v_add_u32_e32 v2, 0x7ad, v154
	s_cselect_b64 s[38:39], -1, 0
	v_cmp_gt_u32_e64 s[40:41], s26, v2
	v_add_u32_e32 v2, 0x7a0, v154
	s_or_b64 s[72:73], s[38:39], s[30:31]
	v_cmp_gt_u32_e64 s[38:39], s26, v2
	v_add_u32_e32 v2, 0x79f, v154
	v_cmp_gt_u32_e64 s[66:67], s26, v2
	v_add_u32_e32 v2, 0x79e, v154
	v_cmp_gt_u32_e64 s[60:61], s26, v2
	v_add_u32_e32 v2, 0x79d, v154
	v_cmp_gt_u32_e64 s[56:57], s26, v2
	s_waitcnt lgkmcnt(3)
	v_mfma_f32_16x16x32_bf16 v[84:87], v[84:87], v[4:7], 0
	v_add_u32_e32 v2, 0x790, v154
	v_cmp_gt_u32_e64 s[64:65], s26, v2
	v_add_u32_e32 v2, 0x78f, v154
	s_waitcnt lgkmcnt(2)
	v_mfma_f32_16x16x32_bf16 v[88:91], v[88:91], v[4:7], 0
	v_cmp_gt_u32_e64 s[68:69], s26, v2
	v_add_u32_e32 v2, 0x78e, v154
	v_mul_f32_e32 v157, v129, v3
	s_waitcnt lgkmcnt(1)
	v_mfma_f32_16x16x32_bf16 v[100:103], v[92:95], v[4:7], 0
	v_cmp_gt_u32_e64 s[62:63], s26, v2
	v_add_u32_e32 v2, 0x78d, v154
	v_add_u32_e32 v3, 0x7c0, v154
	s_waitcnt lgkmcnt(0)
	v_mfma_f32_16x16x32_bf16 v[110:113], v[96:99], v[4:7], 0
	v_cmp_gt_u32_e64 s[58:59], s26, v2
	v_fmamk_f32 v97, v84, 0x3e8293ee, v157
	v_fmamk_f32 v2, v85, 0x3e8293ee, v157
	v_fmamk_f32 v105, v86, 0x3e8293ee, v157
	v_fmamk_f32 v106, v87, 0x3e8293ee, v157
	v_cmp_gt_u32_e64 s[54:55], s26, v3
	v_fmac_f32_e32 v97, 0, v129
	s_mov_b64 s[30:31], -1
	s_and_b64 vcc, exec, s[72:73]
	v_add_f32_e32 v109, v129, v2
	v_fmac_f32_e32 v105, 2.0, v129
	v_fmac_f32_e32 v106, 0x40400000, v129
	v_fmamk_f32 v108, v88, 0x3e8293ee, v157
	v_fmamk_f32 v107, v89, 0x3e8293ee, v157
	v_fmamk_f32 v104, v90, 0x3e8293ee, v157
	v_fmamk_f32 v99, v91, 0x3e8293ee, v157
	v_fmamk_f32 v98, v100, 0x3e8293ee, v157
	v_fmamk_f32 v96, v101, 0x3e8293ee, v157
	v_fmamk_f32 v95, v102, 0x3e8293ee, v157
	v_fmamk_f32 v94, v103, 0x3e8293ee, v157
	v_fmamk_f32 v93, v110, 0x3e8293ee, v157
	v_fmamk_f32 v92, v111, 0x3e8293ee, v157
	v_fmamk_f32 v91, v112, 0x3e8293ee, v157
	v_fmamk_f32 v90, v113, 0x3e8293ee, v157
	s_cbranch_vccz .LBB0_212
	v_cndmask_b32_e64 v2, v226, v97, s[54:55]
	v_exp_f32_e32 v100, v2
	v_cndmask_b32_e64 v2, v226, v109, s[48:49]
	v_exp_f32_e32 v101, v2
	v_cndmask_b32_e64 v2, v226, v105, s[50:51]
	v_exp_f32_e32 v102, v2
	v_cndmask_b32_e64 v2, v226, v106, s[52:53]
	v_exp_f32_e32 v103, v2
	v_fmamk_f32 v2, v129, 0x41800000, v108
	v_cndmask_b32_e64 v2, v226, v2, s[46:47]
	v_exp_f32_e32 v110, v2
	v_fmamk_f32 v2, v129, 0x41880000, v107
	v_cndmask_b32_e64 v2, v226, v2, s[44:45]
	v_exp_f32_e32 v111, v2
	v_fmamk_f32 v2, v129, 0x41900000, v104
	v_cndmask_b32_e64 v2, v226, v2, s[42:43]
	v_exp_f32_e32 v112, v2
	v_fmamk_f32 v2, v129, 0x41980000, v99
	v_cndmask_b32_e64 v2, v226, v2, s[40:41]
	v_exp_f32_e32 v113, v2
	v_fmamk_f32 v2, v129, 0x42000000, v98
	v_fmamk_f32 v3, v129, 0x42040000, v96
	v_fmamk_f32 v84, v129, 0x42080000, v95
	v_fmamk_f32 v85, v129, 0x420c0000, v94
	v_fmamk_f32 v86, v129, 0x42400000, v93
	v_fmamk_f32 v87, v129, 0x42440000, v92
	v_fmamk_f32 v88, v129, 0x42480000, v91
	v_fmamk_f32 v89, v129, 0x424c0000, v90
	v_cndmask_b32_e64 v2, v226, v2, s[38:39]
	v_cndmask_b32_e64 v3, v226, v3, s[66:67]
	v_cndmask_b32_e64 v84, v226, v84, s[60:61]
	v_cndmask_b32_e64 v85, v226, v85, s[56:57]
	v_cndmask_b32_e64 v86, v226, v86, s[64:65]
	v_cndmask_b32_e64 v87, v226, v87, s[68:69]
	v_cndmask_b32_e64 v88, v226, v88, s[62:63]
	v_cndmask_b32_e64 v89, v226, v89, s[58:59]
	v_exp_f32_e32 v2, v2
	v_exp_f32_e32 v3, v3
	v_exp_f32_e32 v84, v84
	v_exp_f32_e32 v85, v85
	v_exp_f32_e32 v86, v86
	v_exp_f32_e32 v87, v87
	v_exp_f32_e32 v88, v88
	v_exp_f32_e32 v89, v89
	v_cvt_pk_bf16_f32 v100, v100, v101
	v_cvt_pk_bf16_f32 v101, v102, v103
	v_cvt_pk_bf16_f32 v102, v110, v111
	v_cvt_pk_bf16_f32 v103, v112, v113
	s_mov_b64 s[30:31], 0

; template <bool MASKED>
; __device__ __forceinline__ void sm_step(f32x4 (&S)[4], float c1, float slope2, float tb, int kbase, int tqn,
;                                         int window, bool selok, bf16x8 (&pb)[2]) {
; #pragma unroll
;   for (int mt = 0; mt < 4; ++mt)
; #pragma unroll
;     for (int r = 0; r < 4; ++r) {
;       float u = fmaf(slope2, (float)(mt * 16 + r), fmaf(S[mt][r], c1, tb));
;       if (MASKED) {
;         int dist = tqn - (kbase + mt * 16 + r);
;         bool valid = (dist >= 0) && (dist < window) && selok;
;         u = valid ? u : -1e30f;
;       }
;       S[mt][r] = fexp2(u);
;     }
; #pragma unroll
;     ...
;     for (int hk = 0; hk < TK; ++hk) {
;     const u16* cK = sK + stg * FST + hk * TSZ;
;     const u16* cV = cK + 64 * 72;
;     const int k0 = (kt + hk) * 64;
;     if (k0 <= qhi && (qlo - (k0 + 63)) < window) {
;       bool full = (k0 + 63 <= qlo) && (qhi - k0 < window);
;       const bool rowfull = SEL && full;
;       bool selok[NQ];
; #pragma unroll
;       for (int n = 0; n < NQ; ++n) selok[n] = true;
;       if (SEL) {
;         bool all = true;
; #pragma unroll
;         for (int n = 0; n < NQ; ++n) { selok[n] = ((selq[n] >> kt) & 1u) != 0; all = all && selok[n]; }
;         full = full && __all(all);
;       }
;       const int kbase = k0 + quad * 4;
; #pragma unroll
;       for (int mp = 0; mp < NMAP; ++mp) {
; #pragma unroll
;         for (int n = 0; n < NQ; ++n) {
;           f32x4 S[4];
; #pragma unroll
;           for (int mt = 0; mt < 4; ++mt) S[mt] = f32x4{0.f, 0.f, 0.f, 0.f};
; #pragma unroll
;           for (int ks = 0; ks < 2; ++ks) {
;             if (NMAP == 2 && ks != mp) continue;
; #pragma unroll
;             for (int mt = 0; mt < 4; ++mt) {
;               bf16x8 a = *(const bf16x8*)(cK + (mt * 16 + l15) * 64 + (((ks * 4 + quad) ^ ((l15 >> 1) & 7)) * 8));
;               S[mt] = mfma16(a, qf[n][ks], S[mt]);
;             }
;           }
;           bf16x8 pb[2];
;           const float tb = slope2 * (float)(kbase - tq[n]);
;           if (full || rowfull) {
;             sm_step<false>(S, c1, slope2, tb, kbase, tq[n], window, true, pb);
;             if (SEL && !full && !selok[n]) {
;               pb[0] = bf16x8{0, 0, 0, 0, 0, 0, 0, 0}; pb[1] = bf16x8{0, 0, 0, 0, 0, 0, 0, 0};
;             }
;           } else sm_step<true>(S, c1, slope2, tb, kbase, tq[n], window, selok[n], pb);
.LBB0_219:
	s_add_i32 s29, s80, 64
	s_cmp_gt_i32 s29, s77
	s_cbranch_scc1 .LBB0_204
	s_add_i32 s29, s80, 0x7f
	s_cmp_le_i32 s29, s74
	s_cbranch_scc1 .Ldiff_t1_fast
	v_add_u32_e32 v2, 0xfffff880, v156
	v_cvt_f32_i32_e32 v3, v2
	v_cmp_lt_u32_e64 s[56:57], s34, v2
	v_add_u32_e32 v2, 0x77e, v154
	v_cmp_gt_u32_e64 s[58:59], s26, v2
	v_add_u32_e32 v2, 0x77d, v154
	ds_read_b128 v[84:87], v155 offset:18432
	ds_read_b128 v[88:91], v155 offset:20480
	v_cmp_gt_u32_e64 s[60:61], s26, v2
	v_add_u32_e32 v2, 0x770, v154
	ds_read_b128 v[92:95], v155 offset:22528
	ds_read_b128 v[96:99], v155 offset:24576
	v_cmp_gt_u32_e64 s[50:51], s26, v2
	v_add_u32_e32 v2, 0x76f, v154
	v_cmp_gt_u32_e64 s[46:47], s26, v2
	v_add_u32_e32 v2, 0x76e, v154
	v_cmp_gt_u32_e64 s[42:43], s26, v2
	v_add_u32_e32 v2, 0x76d, v154
	v_cmp_gt_u32_e64 s[40:41], s26, v2
	v_add_u32_e32 v2, 0x760, v154
	v_cmp_gt_u32_e64 s[38:39], s26, v2
	v_add_u32_e32 v2, 0x75f, v154
	v_cmp_gt_u32_e64 s[68:69], s26, v2
	v_add_u32_e32 v2, 0x75e, v154
	v_cmp_gt_u32_e64 s[62:63], s26, v2
	v_add_u32_e32 v2, 0x75d, v154
	v_cmp_gt_u32_e64 s[52:53], s26, v2
	s_waitcnt lgkmcnt(3)
	v_mfma_f32_16x16x32_bf16 v[84:87], v[84:87], v[4:7], 0
	v_add_u32_e32 v2, 0x750, v154
	v_cmp_gt_u32_e64 s[54:55], s26, v2
	v_add_u32_e32 v2, 0x74f, v154
	s_waitcnt lgkmcnt(2)
	v_mfma_f32_16x16x32_bf16 v[88:91], v[88:91], v[4:7], 0
	s_add_i32 s29, s80, 0x7f
	v_cmp_gt_u32_e64 s[64:65], s26, v2
	v_add_u32_e32 v2, 0x74e, v154
	s_waitcnt lgkmcnt(1)
	v_mfma_f32_16x16x32_bf16 v[100:103], v[92:95], v[4:7], 0
	s_cmp_le_i32 s29, s74
	v_mul_f32_e32 v156, v129, v3
	v_cmp_gt_u32_e64 s[48:49], s26, v2
	s_waitcnt lgkmcnt(0)
	v_mfma_f32_16x16x32_bf16 v[110:113], v[96:99], v[4:7], 0
	v_add_u32_e32 v2, 0x74d, v154
	s_cselect_b64 s[72:73], -1, 0
	v_add_u32_e32 v3, 0x780, v154
	v_cmp_gt_u32_e64 s[44:45], s26, v2
	v_fmamk_f32 v104, v84, 0x3e8293ee, v156
	v_fmamk_f32 v2, v85, 0x3e8293ee, v156
	v_fmamk_f32 v107, v86, 0x3e8293ee, v156
	v_fmamk_f32 v106, v87, 0x3e8293ee, v156
	v_cmp_gt_u32_e64 s[66:67], s26, v3
	v_fmac_f32_e32 v104, 0, v129
	s_mov_b64 s[30:31], -1
	s_and_b64 vcc, exec, s[72:73]
	v_add_f32_e32 v109, v129, v2
	v_fmac_f32_e32 v107, 2.0, v129
	v_fmac_f32_e32 v106, 0x40400000, v129
	v_fmamk_f32 v108, v88, 0x3e8293ee, v156
	v_fmamk_f32 v105, v89, 0x3e8293ee, v156
	v_fmamk_f32 v99, v90, 0x3e8293ee, v156
	v_fmamk_f32 v98, v91, 0x3e8293ee, v156
	v_fmamk_f32 v97, v100, 0x3e8293ee, v156
	v_fmamk_f32 v96, v101, 0x3e8293ee, v156
	v_fmamk_f32 v95, v102, 0x3e8293ee, v156
	v_fmamk_f32 v94, v103, 0x3e8293ee, v156
	v_fmamk_f32 v93, v110, 0x3e8293ee, v156
	v_fmamk_f32 v92, v111, 0x3e8293ee, v156
	v_fmamk_f32 v91, v112, 0x3e8293ee, v156
	v_fmamk_f32 v90, v113, 0x3e8293ee, v156
	s_cbranch_vccz .LBB0_222
.Ldiff_t1_full:
	v_fmamk_f32 v2, v129, 0x41800000, v108
	v_exp_f32_e32 v110, v2
	v_fmamk_f32 v2, v129, 0x41880000, v105
	v_exp_f32_e32 v111, v2
	v_fmamk_f32 v2, v129, 0x41900000, v99
	v_exp_f32_e32 v112, v2
	v_fmamk_f32 v2, v129, 0x41980000, v98
	v_exp_f32_e32 v100, v104
	v_exp_f32_e32 v101, v109
	v_exp_f32_e32 v102, v107
	v_exp_f32_e32 v103, v106
	v_exp_f32_e32 v113, v2
	v_fmamk_f32 v2, v129, 0x42000000, v97
	v_fmamk_f32 v3, v129, 0x42040000, v96
	v_fmamk_f32 v84, v129, 0x42080000, v95
	v_fmamk_f32 v85, v129, 0x420c0000, v94
	v_fmamk_f32 v86, v129, 0x42400000, v93
	v_fmamk_f32 v87, v129, 0x42440000, v92
	v_fmamk_f32 v88, v129, 0x42480000, v91
	v_fmamk_f32 v89, v129, 0x424c0000, v90
	v_exp_f32_e32 v2, v2
	v_exp_f32_e32 v3, v3
	v_exp_f32_e32 v84, v84
	v_exp_f32_e32 v85, v85
	v_exp_f32_e32 v86, v86
	v_exp_f32_e32 v87, v87
	v_exp_f32_e32 v88, v88
	v_exp_f32_e32 v89, v89
	v_cvt_pk_bf16_f32 v100, v100, v101
	v_cvt_pk_bf16_f32 v101, v102, v103
	v_cvt_pk_bf16_f32 v102, v110, v111
	v_cvt_pk_bf16_f32 v103, v112, v113
	s_mov_b64 s[30:31], 0

; template <bool MASKED>
; __device__ __forceinline__ void sm_step(f32x4 (&S)[4], float c1, float slope2, float tb, int kbase, int tqn,
;                                         int window, bool selok, bf16x8 (&pb)[2]) {
; #pragma unroll
;   for (int mt = 0; mt < 4; ++mt)
; #pragma unroll
;     for (int r = 0; r < 4; ++r) {
;       float u = fmaf(slope2, (float)(mt * 16 + r), fmaf(S[mt][r], c1, tb));
;       if (MASKED) {
;         int dist = tqn - (kbase + mt * 16 + r);
;         bool valid = (dist >= 0) && (dist < window) && selok;
;         u = valid ? u : -1e30f;
;       }
;       S[mt][r] = fexp2(u);
;     }
; #pragma unroll
;     ...
;     for (int hk = 0; hk < TK; ++hk) {
;     const u16* cK = sK + stg * FST + hk * TSZ;
;     const u16* cV = cK + 64 * 72;
;     const int k0 = (kt + hk) * 64;
;     if (k0 <= qhi && (qlo - (k0 + 63)) < window) {
;       bool full = (k0 + 63 <= qlo) && (qhi - k0 < window);
;       const bool rowfull = SEL && full;
;       bool selok[NQ];
; #pragma unroll
;       for (int n = 0; n < NQ; ++n) selok[n] = true;
;       if (SEL) {
;         bool all = true;
; #pragma unroll
;         for (int n = 0; n < NQ; ++n) { selok[n] = ((selq[n] >> kt) & 1u) != 0; all = all && selok[n]; }
;         full = full && __all(all);
;       }
;       const int kbase = k0 + quad * 4;
; #pragma unroll
;       for (int mp = 0; mp < NMAP; ++mp) {
; #pragma unroll
;         for (int n = 0; n < NQ; ++n) {
;           f32x4 S[4];
; #pragma unroll
;           for (int mt = 0; mt < 4; ++mt) S[mt] = f32x4{0.f, 0.f, 0.f, 0.f};
; #pragma unroll
;           for (int ks = 0; ks < 2; ++ks) {
;             if (NMAP == 2 && ks != mp) continue;
; #pragma unroll
;             for (int mt = 0; mt < 4; ++mt) {
;               bf16x8 a = *(const bf16x8*)(cK + (mt * 16 + l15) * 64 + (((ks * 4 + quad) ^ ((l15 >> 1) & 7)) * 8));
;               S[mt] = mfma16(a, qf[n][ks], S[mt]);
;             }
;           }
;           bf16x8 pb[2];
;           const float tb = slope2 * (float)(kbase - tq[n]);
;           if (full || rowfull) {
;             sm_step<false>(S, c1, slope2, tb, kbase, tq[n], window, true, pb);
;             if (SEL && !full && !selok[n]) {
;               pb[0] = bf16x8{0, 0, 0, 0, 0, 0, 0, 0}; pb[1] = bf16x8{0, 0, 0, 0, 0, 0, 0, 0};
;             }
;           } else sm_step<true>(S, c1, slope2, tb, kbase, tq[n], window, selok[n], pb);
.Ldiff_t0_fast:
	v_add_u32_e32 v2, 0xfffff840, v156
	v_cvt_f32_i32_e32 v3, v2
	ds_read_b128 v[84:87], v155
	ds_read_b128 v[88:91], v155 offset:2048
	ds_read_b128 v[92:95], v155 offset:4096
	ds_read_b128 v[96:99], v155 offset:6144
	s_add_i32 s29, s80, 63
	s_cmp_eq_u32 s35, s79
	s_cselect_b64 s[30:31], -1, 0
	s_cmp_gt_i32 s29, s74
	s_cselect_b64 s[38:39], -1, 0
	s_or_b64 s[72:73], s[38:39], s[30:31]
	s_waitcnt lgkmcnt(3)
	v_mfma_f32_16x16x32_bf16 v[84:87], v[84:87], v[4:7], 0
	s_waitcnt lgkmcnt(2)
	v_mfma_f32_16x16x32_bf16 v[88:91], v[88:91], v[4:7], 0
	v_mul_f32_e32 v157, v129, v3
	s_waitcnt lgkmcnt(1)
	v_mfma_f32_16x16x32_bf16 v[100:103], v[92:95], v[4:7], 0
	s_waitcnt lgkmcnt(0)
	v_mfma_f32_16x16x32_bf16 v[110:113], v[96:99], v[4:7], 0
	s_nop 3
	v_fmamk_f32 v97, v84, 0x3e8293ee, v157
	v_fmamk_f32 v2, v85, 0x3e8293ee, v157
	v_fmamk_f32 v105, v86, 0x3e8293ee, v157
	v_fmamk_f32 v106, v87, 0x3e8293ee, v157
	v_fmac_f32_e32 v97, 0, v129
	s_mov_b64 s[30:31], -1
	s_and_b64 vcc, exec, s[72:73]
	v_add_f32_e32 v109, v129, v2
	v_fmac_f32_e32 v105, 2.0, v129
	v_fmac_f32_e32 v106, 0x40400000, v129
	v_fmamk_f32 v108, v88, 0x3e8293ee, v157
	v_fmamk_f32 v107, v89, 0x3e8293ee, v157
	v_fmamk_f32 v104, v90, 0x3e8293ee, v157
	v_fmamk_f32 v99, v91, 0x3e8293ee, v157
	v_fmamk_f32 v98, v100, 0x3e8293ee, v157
	v_fmamk_f32 v96, v101, 0x3e8293ee, v157
	v_fmamk_f32 v95, v102, 0x3e8293ee, v157
	v_fmamk_f32 v94, v103, 0x3e8293ee, v157
	v_fmamk_f32 v93, v110, 0x3e8293ee, v157
	v_fmamk_f32 v92, v111, 0x3e8293ee, v157
	v_fmamk_f32 v91, v112, 0x3e8293ee, v157
	v_fmamk_f32 v90, v113, 0x3e8293ee, v157
	s_branch .LBB0_212
.Ldiff_t1_fast:
	v_add_u32_e32 v2, 0xfffff880, v156
	v_cvt_f32_i32_e32 v3, v2
	ds_read_b128 v[84:87], v155 offset:18432
	ds_read_b128 v[88:91], v155 offset:20480
	ds_read_b128 v[92:95], v155 offset:22528
	ds_read_b128 v[96:99], v155 offset:24576
	s_waitcnt lgkmcnt(3)
	v_mfma_f32_16x16x32_bf16 v[84:87], v[84:87], v[4:7], 0
	s_waitcnt lgkmcnt(2)
	v_mfma_f32_16x16x32_bf16 v[88:91], v[88:91], v[4:7], 0
	s_add_i32 s29, s80, 0x7f
	s_waitcnt lgkmcnt(1)
	v_mfma_f32_16x16x32_bf16 v[100:103], v[92:95], v[4:7], 0
	s_cmp_le_i32 s29, s74
	v_mul_f32_e32 v156, v129, v3
	s_waitcnt lgkmcnt(0)
	v_mfma_f32_16x16x32_bf16 v[110:113], v[96:99], v[4:7], 0
	s_cselect_b64 s[72:73], -1, 0
	s_nop 3
	v_fmamk_f32 v104, v84, 0x3e8293ee, v156
	v_fmamk_f32 v2, v85, 0x3e8293ee, v156
	v_fmamk_f32 v107, v86, 0x3e8293ee, v156
	v_fmamk_f32 v106, v87, 0x3e8293ee, v156
	v_fmac_f32_e32 v104, 0, v129
	s_mov_b64 s[30:31], -1
	s_and_b64 vcc, exec, s[72:73]
	v_add_f32_e32 v109, v129, v2
	v_fmac_f32_e32 v107, 2.0, v129
	v_fmac_f32_e32 v106, 0x40400000, v129
	v_fmamk_f32 v108, v88, 0x3e8293ee, v156
	v_fmamk_f32 v105, v89, 0x3e8293ee, v156
	v_fmamk_f32 v99, v90, 0x3e8293ee, v156
	v_fmamk_f32 v98, v91, 0x3e8293ee, v156
	v_fmamk_f32 v97, v100, 0x3e8293ee, v156
	v_fmamk_f32 v96, v101, 0x3e8293ee, v156
	v_fmamk_f32 v95, v102, 0x3e8293ee, v156
	v_fmamk_f32 v94, v103, 0x3e8293ee, v156
	v_fmamk_f32 v93, v110, 0x3e8293ee, v156
	v_fmamk_f32 v92, v111, 0x3e8293ee, v156
	v_fmamk_f32 v91, v112, 0x3e8293ee, v156
	v_fmamk_f32 v90, v113, 0x3e8293ee, v156
	s_branch .Ldiff_t1_full

; __device__ __forceinline__ float bf2f(u16 b) { return __uint_as_float(((unsigned)b) << 16); }
; __device__ void item_compress(const Params& p, int layer, int kv, int b, int g, int ct, unsigned char* smem) {
;     ...
;   const u16* src = P_H + ((size_t)b * SEQ + (size_t)(cvalid ? 16 * c : 0)) * HS + col + quad * 8;
;   const u16* wb = w1t + (size_t)l15 * 2048 + quad * 8;
;   f32x4 acc[8];
; #pragma unroll
;   for (int j = 0; j < 8; ++j) acc[j] = f32x4{0.f, 0.f, 0.f, 0.f};
; #pragma unroll 4
;   for (int ii = 0; ii < 8; ++ii) {
;     const int i = wave * 8 + ii;
; #pragma unroll
;     for (int ks = 0; ks < 2; ++ks) {
;       uint4 raw = *(const uint4*)(src + (size_t)i * HS + ks * 32);
;       const float* pp = pe + i * 64 + ks * 32 + quad * 8;
;       float4 p0 = *(const float4*)pp, p1 = *(const float4*)(pp + 4);
;       bf16x8 a = pack8(bf2f((u16)(raw.x & 0xffff)) + p0.x, bf2f((u16)(raw.x >> 16)) + p0.y,
;                        bf2f((u16)(raw.y & 0xffff)) + p0.z, bf2f((u16)(raw.y >> 16)) + p0.w,
;                        bf2f((u16)(raw.z & 0xffff)) + p1.x, bf2f((u16)(raw.z >> 16)) + p1.y,
;                        bf2f((u16)(raw.w & 0xffff)) + p1.z, bf2f((u16)(raw.w >> 16)) + p1.w);
; #pragma unroll
;       for (int j = 0; j < 8; ++j) {
;         bf16x8 bfr = *(const bf16x8*)(wb + (size_t)(j * 16) * 2048 + i * 64 + ks * 32);
;         acc[j] = mfma16(a, bfr, acc[j]);
;       }
;     }
.LBB0_233:
	v_lshl_add_u64 v[52:53], v[46:47], 0, v[0:1]
	v_add_co_u32_e32 v54, vcc, 0x10000, v52
	s_nop 1
	v_addc_co_u32_e32 v55, vcc, 0, v53, vcc
	v_add_co_u32_e32 v56, vcc, 0x20000, v52
	s_nop 1
	v_addc_co_u32_e32 v57, vcc, 0, v53, vcc
	v_add_co_u32_e32 v58, vcc, 0x30000, v52
	s_nop 1
	v_addc_co_u32_e32 v59, vcc, 0, v53, vcc
	v_add_co_u32_e32 v60, vcc, 0x40000, v52
	s_nop 1
	v_addc_co_u32_e32 v61, vcc, 0, v53, vcc
	v_add_co_u32_e32 v62, vcc, 0x50000, v52
	s_nop 1
	v_addc_co_u32_e32 v63, vcc, 0, v53, vcc
	v_add_co_u32_e32 v64, vcc, 0x60000, v52
	s_nop 1
	v_addc_co_u32_e32 v65, vcc, 0, v53, vcc
	v_add_co_u32_e32 v66, vcc, 0x70000, v52
	s_nop 1
	v_addc_co_u32_e32 v67, vcc, 0, v53, vcc
	v_lshl_add_u64 v[68:69], v[48:49], 0, v[0:1]
	v_add_co_u32_e32 v68, vcc, 0x4924000, v68
	s_nop 1
	v_addc_co_u32_e32 v69, vcc, 0, v69, vcc
	v_mov_b32_e32 v70, v50
	v_mov_b32_e32 v71, v51
	global_load_dwordx4 v[80:83], v[68:69], off offset:1024
	global_load_dwordx4 v[84:87], v[70:71], off offset:0
	global_load_dwordx4 v[88:91], v[70:71], off offset:16
	global_load_dwordx4 v[92:95], v[52:53], off offset:0
	global_load_dwordx4 v[96:99], v[54:55], off offset:0
	global_load_dwordx4 v[100:103], v[56:57], off offset:0
	global_load_dwordx4 v[104:107], v[58:59], off offset:0
	global_load_dwordx4 v[108:111], v[60:61], off offset:0
	global_load_dwordx4 v[112:115], v[62:63], off offset:0
	global_load_dwordx4 v[116:119], v[64:65], off offset:0
	global_load_dwordx4 v[120:123], v[66:67], off offset:0
	global_load_dwordx4 v[124:127], v[68:69], off offset:1088
	global_load_dwordx4 v[128:131], v[70:71], off offset:128
	global_load_dwordx4 v[132:135], v[70:71], off offset:144
	global_load_dwordx4 v[136:139], v[52:53], off offset:64
	global_load_dwordx4 v[140:143], v[54:55], off offset:64
	global_load_dwordx4 v[144:147], v[56:57], off offset:64
	global_load_dwordx4 v[148:151], v[58:59], off offset:64
	global_load_dwordx4 v[152:155], v[60:61], off offset:64
	global_load_dwordx4 v[156:159], v[62:63], off offset:64
	global_load_dwordx4 v[160:163], v[64:65], off offset:64
	global_load_dwordx4 v[164:167], v[66:67], off offset:64
	v_add_co_u32_e32 v68, vcc, 0x1d00, v68
	s_nop 1
	v_addc_co_u32_e32 v69, vcc, 0, v69, vcc
	global_load_dwordx4 v[168:171], v[68:69], off offset:1024
	global_load_dwordx4 v[172:175], v[70:71], off offset:256
	global_load_dwordx4 v[176:179], v[70:71], off offset:272
	global_load_dwordx4 v[180:183], v[52:53], off offset:128
	global_load_dwordx4 v[184:187], v[54:55], off offset:128
	global_load_dwordx4 v[188:191], v[56:57], off offset:128
	global_load_dwordx4 v[192:195], v[58:59], off offset:128
	global_load_dwordx4 v[196:199], v[60:61], off offset:128
	global_load_dwordx4 v[200:203], v[62:63], off offset:128
	global_load_dwordx4 v[204:207], v[64:65], off offset:128
	global_load_dwordx4 v[218:221], v[66:67], off offset:128
	s_waitcnt vmcnt(22)
	v_lshlrev_b32_e32 v208, 16, v80
	v_and_b32_e32 v209, 0xffff0000, v80
	v_pk_add_f32 v[84:85], v[84:85], v[208:209]
	v_lshlrev_b32_e32 v208, 16, v81
	v_and_b32_e32 v209, 0xffff0000, v81
	v_pk_add_f32 v[86:87], v[86:87], v[208:209]
	v_lshlrev_b32_e32 v208, 16, v82
	v_and_b32_e32 v209, 0xffff0000, v82
	v_pk_add_f32 v[88:89], v[88:89], v[208:209]
	v_lshlrev_b32_e32 v208, 16, v83
	v_and_b32_e32 v209, 0xffff0000, v83
	v_pk_add_f32 v[90:91], v[90:91], v[208:209]
	v_cvt_pk_bf16_f32 v80, v84, v85
	v_cvt_pk_bf16_f32 v81, v86, v87
	v_cvt_pk_bf16_f32 v82, v88, v89
	v_cvt_pk_bf16_f32 v83, v90, v91
	s_nop 1
	v_mfma_f32_16x16x32_bf16 v[2:5], v[80:83], v[92:95], v[2:5]
	v_mfma_f32_16x16x32_bf16 v[30:33], v[80:83], v[96:99], v[30:33]
	v_mfma_f32_16x16x32_bf16 v[26:29], v[80:83], v[100:103], v[26:29]
	v_mfma_f32_16x16x32_bf16 v[22:25], v[80:83], v[104:107], v[22:25]
	v_mfma_f32_16x16x32_bf16 v[18:21], v[80:83], v[108:111], v[18:21]
	v_mfma_f32_16x16x32_bf16 v[14:17], v[80:83], v[112:115], v[14:17]
	v_mfma_f32_16x16x32_bf16 v[10:13], v[80:83], v[116:119], v[10:13]
	v_mfma_f32_16x16x32_bf16 v[6:9], v[80:83], v[120:123], v[6:9]
	global_load_dwordx4 v[80:83], v[68:69], off offset:1088
	global_load_dwordx4 v[84:87], v[70:71], off offset:384
	global_load_dwordx4 v[88:91], v[70:71], off offset:400
	global_load_dwordx4 v[92:95], v[52:53], off offset:192
	global_load_dwordx4 v[96:99], v[54:55], off offset:192
	global_load_dwordx4 v[100:103], v[56:57], off offset:192
	global_load_dwordx4 v[104:107], v[58:59], off offset:192
	global_load_dwordx4 v[108:111], v[60:61], off offset:192
	global_load_dwordx4 v[112:115], v[62:63], off offset:192
	global_load_dwordx4 v[116:119], v[64:65], off offset:192
	global_load_dwordx4 v[120:123], v[66:67], off offset:192
	v_add_co_u32_e32 v68, vcc, 0x1d00, v68
	s_nop 1
	v_addc_co_u32_e32 v69, vcc, 0, v69, vcc
	s_waitcnt vmcnt(22)
; __device__ __forceinline__ float bf2f(u16 b) { return __uint_as_float(((unsigned)b) << 16); }
; __device__ void item_compress(const Params& p, int layer, int kv, int b, int g, int ct, unsigned char* smem) {
;     ...
;   for (int ii = 0; ii < 8; ++ii) {
;     const int i = wave * 8 + ii;
; #pragma unroll
;     for (int ks = 0; ks < 2; ++ks) {
;       uint4 raw = *(const uint4*)(src + (size_t)i * HS + ks * 32);
;       const float* pp = pe + i * 64 + ks * 32 + quad * 8;
;       float4 p0 = *(const float4*)pp, p1 = *(const float4*)(pp + 4);
;       bf16x8 a = pack8(bf2f((u16)(raw.x & 0xffff)) + p0.x, bf2f((u16)(raw.x >> 16)) + p0.y,
;                        bf2f((u16)(raw.y & 0xffff)) + p0.z, bf2f((u16)(raw.y >> 16)) + p0.w,
;                        bf2f((u16)(raw.z & 0xffff)) + p1.x, bf2f((u16)(raw.z >> 16)) + p1.y,
;                        bf2f((u16)(raw.w & 0xffff)) + p1.z, bf2f((u16)(raw.w >> 16)) + p1.w);
; #pragma unroll
;       for (int j = 0; j < 8; ++j) {
;         bf16x8 bfr = *(const bf16x8*)(wb + (size_t)(j * 16) * 2048 + i * 64 + ks * 32);
;         acc[j] = mfma16(a, bfr, acc[j]);
;       }
;     }
	v_lshlrev_b32_e32 v208, 16, v124
	v_and_b32_e32 v209, 0xffff0000, v124
	v_pk_add_f32 v[128:129], v[128:129], v[208:209]
	v_lshlrev_b32_e32 v208, 16, v125
	v_and_b32_e32 v209, 0xffff0000, v125
	v_pk_add_f32 v[130:131], v[130:131], v[208:209]
	v_lshlrev_b32_e32 v208, 16, v126
	v_and_b32_e32 v209, 0xffff0000, v126
	v_pk_add_f32 v[132:133], v[132:133], v[208:209]
	v_lshlrev_b32_e32 v208, 16, v127
	v_and_b32_e32 v209, 0xffff0000, v127
	v_pk_add_f32 v[134:135], v[134:135], v[208:209]
	v_cvt_pk_bf16_f32 v124, v128, v129
	v_cvt_pk_bf16_f32 v125, v130, v131
	v_cvt_pk_bf16_f32 v126, v132, v133
	v_cvt_pk_bf16_f32 v127, v134, v135
	s_nop 1
	v_mfma_f32_16x16x32_bf16 v[2:5], v[124:127], v[136:139], v[2:5]
	v_mfma_f32_16x16x32_bf16 v[30:33], v[124:127], v[140:143], v[30:33]
	v_mfma_f32_16x16x32_bf16 v[26:29], v[124:127], v[144:147], v[26:29]
	v_mfma_f32_16x16x32_bf16 v[22:25], v[124:127], v[148:151], v[22:25]
	v_mfma_f32_16x16x32_bf16 v[18:21], v[124:127], v[152:155], v[18:21]
	v_mfma_f32_16x16x32_bf16 v[14:17], v[124:127], v[156:159], v[14:17]
	v_mfma_f32_16x16x32_bf16 v[10:13], v[124:127], v[160:163], v[10:13]
	v_mfma_f32_16x16x32_bf16 v[6:9], v[124:127], v[164:167], v[6:9]
	global_load_dwordx4 v[124:127], v[68:69], off offset:1024
	global_load_dwordx4 v[128:131], v[70:71], off offset:512
	global_load_dwordx4 v[132:135], v[70:71], off offset:528
	global_load_dwordx4 v[136:139], v[52:53], off offset:256
	global_load_dwordx4 v[140:143], v[54:55], off offset:256
	global_load_dwordx4 v[144:147], v[56:57], off offset:256
	global_load_dwordx4 v[148:151], v[58:59], off offset:256
	global_load_dwordx4 v[152:155], v[60:61], off offset:256
	global_load_dwordx4 v[156:159], v[62:63], off offset:256
	global_load_dwordx4 v[160:163], v[64:65], off offset:256
	global_load_dwordx4 v[164:167], v[66:67], off offset:256
	s_waitcnt vmcnt(22)
	v_lshlrev_b32_e32 v208, 16, v168
	v_and_b32_e32 v209, 0xffff0000, v168
	v_pk_add_f32 v[172:173], v[172:173], v[208:209]
	v_lshlrev_b32_e32 v208, 16, v169
	v_and_b32_e32 v209, 0xffff0000, v169
	v_pk_add_f32 v[174:175], v[174:175], v[208:209]
	v_lshlrev_b32_e32 v208, 16, v170
	v_and_b32_e32 v209, 0xffff0000, v170
	v_pk_add_f32 v[176:177], v[176:177], v[208:209]
	v_lshlrev_b32_e32 v208, 16, v171
	v_and_b32_e32 v209, 0xffff0000, v171
	v_pk_add_f32 v[178:179], v[178:179], v[208:209]
	v_cvt_pk_bf16_f32 v168, v172, v173
	v_cvt_pk_bf16_f32 v169, v174, v175
	v_cvt_pk_bf16_f32 v170, v176, v177
	v_cvt_pk_bf16_f32 v171, v178, v179
	s_nop 1
	v_mfma_f32_16x16x32_bf16 v[2:5], v[168:171], v[180:183], v[2:5]
	v_mfma_f32_16x16x32_bf16 v[30:33], v[168:171], v[184:187], v[30:33]
	v_mfma_f32_16x16x32_bf16 v[26:29], v[168:171], v[188:191], v[26:29]
	v_mfma_f32_16x16x32_bf16 v[22:25], v[168:171], v[192:195], v[22:25]
	v_mfma_f32_16x16x32_bf16 v[18:21], v[168:171], v[196:199], v[18:21]
	v_mfma_f32_16x16x32_bf16 v[14:17], v[168:171], v[200:203], v[14:17]
	v_mfma_f32_16x16x32_bf16 v[10:13], v[168:171], v[204:207], v[10:13]
	v_mfma_f32_16x16x32_bf16 v[6:9], v[168:171], v[218:221], v[6:9]
	global_load_dwordx4 v[168:171], v[68:69], off offset:1088
	global_load_dwordx4 v[172:175], v[70:71], off offset:640
	global_load_dwordx4 v[176:179], v[70:71], off offset:656
	global_load_dwordx4 v[180:183], v[52:53], off offset:320
	global_load_dwordx4 v[184:187], v[54:55], off offset:320
	global_load_dwordx4 v[188:191], v[56:57], off offset:320
	global_load_dwordx4 v[192:195], v[58:59], off offset:320
	global_load_dwordx4 v[196:199], v[60:61], off offset:320
	global_load_dwordx4 v[200:203], v[62:63], off offset:320
	global_load_dwordx4 v[204:207], v[64:65], off offset:320
	global_load_dwordx4 v[218:221], v[66:67], off offset:320
	v_add_co_u32_e32 v68, vcc, 0x1d00, v68
	s_nop 1
	v_addc_co_u32_e32 v69, vcc, 0, v69, vcc
	s_waitcnt vmcnt(22)
	v_lshlrev_b32_e32 v208, 16, v80
	v_and_b32_e32 v209, 0xffff0000, v80
	v_pk_add_f32 v[84:85], v[84:85], v[208:209]
	v_lshlrev_b32_e32 v208, 16, v81
	v_and_b32_e32 v209, 0xffff0000, v81
	v_pk_add_f32 v[86:87], v[86:87], v[208:209]
	v_lshlrev_b32_e32 v208, 16, v82
	v_and_b32_e32 v209, 0xffff0000, v82
	v_pk_add_f32 v[88:89], v[88:89], v[208:209]
	v_lshlrev_b32_e32 v208, 16, v83
	v_and_b32_e32 v209, 0xffff0000, v83
	v_pk_add_f32 v[90:91], v[90:91], v[208:209]
	v_cvt_pk_bf16_f32 v80, v84, v85
	v_cvt_pk_bf16_f32 v81, v86, v87
	v_cvt_pk_bf16_f32 v82, v88, v89
	v_cvt_pk_bf16_f32 v83, v90, v91
	s_nop 1
	v_mfma_f32_16x16x32_bf16 v[2:5], v[80:83], v[92:95], v[2:5]
	v_mfma_f32_16x16x32_bf16 v[30:33], v[80:83], v[96:99], v[30:33]
	v_mfma_f32_16x16x32_bf16 v[26:29], v[80:83], v[100:103], v[26:29]
	v_mfma_f32_16x16x32_bf16 v[22:25], v[80:83], v[104:107], v[22:25]
	v_mfma_f32_16x16x32_bf16 v[18:21], v[80:83], v[108:111], v[18:21]
	v_mfma_f32_16x16x32_bf16 v[14:17], v[80:83], v[112:115], v[14:17]
	v_mfma_f32_16x16x32_bf16 v[10:13], v[80:83], v[116:119], v[10:13]
	v_mfma_f32_16x16x32_bf16 v[6:9], v[80:83], v[120:123], v[6:9]
	global_load_dwordx4 v[80:83], v[68:69], off offset:1024
	global_load_dwordx4 v[84:87], v[70:71], off offset:768
	global_load_dwordx4 v[88:91], v[70:71], off offset:784
	global_load_dwordx4 v[92:95], v[52:53], off offset:384
	global_load_dwordx4 v[96:99], v[54:55], off offset:384
	global_load_dwordx4 v[100:103], v[56:57], off offset:384
	global_load_dwordx4 v[104:107], v[58:59], off offset:384
	global_load_dwordx4 v[108:111], v[60:61], off offset:384
	global_load_dwordx4 v[112:115], v[62:63], off offset:384
	global_load_dwordx4 v[116:119], v[64:65], off offset:384
	global_load_dwordx4 v[120:123], v[66:67], off offset:384
	s_waitcnt vmcnt(22)
; __device__ __forceinline__ float bf2f(u16 b) { return __uint_as_float(((unsigned)b) << 16); }
; __device__ void item_compress(const Params& p, int layer, int kv, int b, int g, int ct, unsigned char* smem) {
;     ...
;   for (int ii = 0; ii < 8; ++ii) {
;     const int i = wave * 8 + ii;
; #pragma unroll
;     for (int ks = 0; ks < 2; ++ks) {
;       uint4 raw = *(const uint4*)(src + (size_t)i * HS + ks * 32);
;       const float* pp = pe + i * 64 + ks * 32 + quad * 8;
;       float4 p0 = *(const float4*)pp, p1 = *(const float4*)(pp + 4);
;       bf16x8 a = pack8(bf2f((u16)(raw.x & 0xffff)) + p0.x, bf2f((u16)(raw.x >> 16)) + p0.y,
;                        bf2f((u16)(raw.y & 0xffff)) + p0.z, bf2f((u16)(raw.y >> 16)) + p0.w,
;                        bf2f((u16)(raw.z & 0xffff)) + p1.x, bf2f((u16)(raw.z >> 16)) + p1.y,
;                        bf2f((u16)(raw.w & 0xffff)) + p1.z, bf2f((u16)(raw.w >> 16)) + p1.w);
; #pragma unroll
;       for (int j = 0; j < 8; ++j) {
;         bf16x8 bfr = *(const bf16x8*)(wb + (size_t)(j * 16) * 2048 + i * 64 + ks * 32);
;         acc[j] = mfma16(a, bfr, acc[j]);
;       }
;     }
	v_lshlrev_b32_e32 v208, 16, v124
	v_and_b32_e32 v209, 0xffff0000, v124
	v_pk_add_f32 v[128:129], v[128:129], v[208:209]
	v_lshlrev_b32_e32 v208, 16, v125
	v_and_b32_e32 v209, 0xffff0000, v125
	v_pk_add_f32 v[130:131], v[130:131], v[208:209]
	v_lshlrev_b32_e32 v208, 16, v126
	v_and_b32_e32 v209, 0xffff0000, v126
	v_pk_add_f32 v[132:133], v[132:133], v[208:209]
	v_lshlrev_b32_e32 v208, 16, v127
	v_and_b32_e32 v209, 0xffff0000, v127
	v_pk_add_f32 v[134:135], v[134:135], v[208:209]
	v_cvt_pk_bf16_f32 v124, v128, v129
	v_cvt_pk_bf16_f32 v125, v130, v131
	v_cvt_pk_bf16_f32 v126, v132, v133
	v_cvt_pk_bf16_f32 v127, v134, v135
	s_nop 1
	v_mfma_f32_16x16x32_bf16 v[2:5], v[124:127], v[136:139], v[2:5]
	v_mfma_f32_16x16x32_bf16 v[30:33], v[124:127], v[140:143], v[30:33]
	v_mfma_f32_16x16x32_bf16 v[26:29], v[124:127], v[144:147], v[26:29]
	v_mfma_f32_16x16x32_bf16 v[22:25], v[124:127], v[148:151], v[22:25]
	v_mfma_f32_16x16x32_bf16 v[18:21], v[124:127], v[152:155], v[18:21]
	v_mfma_f32_16x16x32_bf16 v[14:17], v[124:127], v[156:159], v[14:17]
	v_mfma_f32_16x16x32_bf16 v[10:13], v[124:127], v[160:163], v[10:13]
	v_mfma_f32_16x16x32_bf16 v[6:9], v[124:127], v[164:167], v[6:9]
	global_load_dwordx4 v[124:127], v[68:69], off offset:1088
	global_load_dwordx4 v[128:131], v[70:71], off offset:896
	global_load_dwordx4 v[132:135], v[70:71], off offset:912
	global_load_dwordx4 v[136:139], v[52:53], off offset:448
	global_load_dwordx4 v[140:143], v[54:55], off offset:448
	global_load_dwordx4 v[144:147], v[56:57], off offset:448
	global_load_dwordx4 v[148:151], v[58:59], off offset:448
	global_load_dwordx4 v[152:155], v[60:61], off offset:448
	global_load_dwordx4 v[156:159], v[62:63], off offset:448
	global_load_dwordx4 v[160:163], v[64:65], off offset:448
	global_load_dwordx4 v[164:167], v[66:67], off offset:448
	v_add_co_u32_e32 v68, vcc, 0x1d00, v68
	s_nop 1
	v_addc_co_u32_e32 v69, vcc, 0, v69, vcc
	s_waitcnt vmcnt(22)
	v_lshlrev_b32_e32 v208, 16, v168
	v_and_b32_e32 v209, 0xffff0000, v168
	v_pk_add_f32 v[172:173], v[172:173], v[208:209]
	v_lshlrev_b32_e32 v208, 16, v169
	v_and_b32_e32 v209, 0xffff0000, v169
	v_pk_add_f32 v[174:175], v[174:175], v[208:209]
	v_lshlrev_b32_e32 v208, 16, v170
	v_and_b32_e32 v209, 0xffff0000, v170
	v_pk_add_f32 v[176:177], v[176:177], v[208:209]
	v_lshlrev_b32_e32 v208, 16, v171
	v_and_b32_e32 v209, 0xffff0000, v171
	v_pk_add_f32 v[178:179], v[178:179], v[208:209]
	v_cvt_pk_bf16_f32 v168, v172, v173
	v_cvt_pk_bf16_f32 v169, v174, v175
	v_cvt_pk_bf16_f32 v170, v176, v177
	v_cvt_pk_bf16_f32 v171, v178, v179
	s_nop 1
	v_mfma_f32_16x16x32_bf16 v[2:5], v[168:171], v[180:183], v[2:5]
	v_mfma_f32_16x16x32_bf16 v[30:33], v[168:171], v[184:187], v[30:33]
	v_mfma_f32_16x16x32_bf16 v[26:29], v[168:171], v[188:191], v[26:29]
	v_mfma_f32_16x16x32_bf16 v[22:25], v[168:171], v[192:195], v[22:25]
	v_mfma_f32_16x16x32_bf16 v[18:21], v[168:171], v[196:199], v[18:21]
	v_mfma_f32_16x16x32_bf16 v[14:17], v[168:171], v[200:203], v[14:17]
	v_mfma_f32_16x16x32_bf16 v[10:13], v[168:171], v[204:207], v[10:13]
	v_mfma_f32_16x16x32_bf16 v[6:9], v[168:171], v[218:221], v[6:9]
	global_load_dwordx4 v[168:171], v[68:69], off offset:1024
	global_load_dwordx4 v[172:175], v[70:71], off offset:1024
	global_load_dwordx4 v[176:179], v[70:71], off offset:1040
	global_load_dwordx4 v[180:183], v[52:53], off offset:512
	global_load_dwordx4 v[184:187], v[54:55], off offset:512
	global_load_dwordx4 v[188:191], v[56:57], off offset:512
	global_load_dwordx4 v[192:195], v[58:59], off offset:512
	global_load_dwordx4 v[196:199], v[60:61], off offset:512
	global_load_dwordx4 v[200:203], v[62:63], off offset:512
	global_load_dwordx4 v[204:207], v[64:65], off offset:512
	global_load_dwordx4 v[218:221], v[66:67], off offset:512
	s_waitcnt vmcnt(22)
	v_lshlrev_b32_e32 v208, 16, v80
	v_and_b32_e32 v209, 0xffff0000, v80
	v_pk_add_f32 v[84:85], v[84:85], v[208:209]
	v_lshlrev_b32_e32 v208, 16, v81
	v_and_b32_e32 v209, 0xffff0000, v81
	v_pk_add_f32 v[86:87], v[86:87], v[208:209]
	v_lshlrev_b32_e32 v208, 16, v82
	v_and_b32_e32 v209, 0xffff0000, v82
	v_pk_add_f32 v[88:89], v[88:89], v[208:209]
	v_lshlrev_b32_e32 v208, 16, v83
	v_and_b32_e32 v209, 0xffff0000, v83
	v_pk_add_f32 v[90:91], v[90:91], v[208:209]
	v_cvt_pk_bf16_f32 v80, v84, v85
	v_cvt_pk_bf16_f32 v81, v86, v87
	v_cvt_pk_bf16_f32 v82, v88, v89
	v_cvt_pk_bf16_f32 v83, v90, v91
	s_nop 1
	v_mfma_f32_16x16x32_bf16 v[2:5], v[80:83], v[92:95], v[2:5]
	v_mfma_f32_16x16x32_bf16 v[30:33], v[80:83], v[96:99], v[30:33]
	v_mfma_f32_16x16x32_bf16 v[26:29], v[80:83], v[100:103], v[26:29]
	v_mfma_f32_16x16x32_bf16 v[22:25], v[80:83], v[104:107], v[22:25]
	v_mfma_f32_16x16x32_bf16 v[18:21], v[80:83], v[108:111], v[18:21]
	v_mfma_f32_16x16x32_bf16 v[14:17], v[80:83], v[112:115], v[14:17]
	v_mfma_f32_16x16x32_bf16 v[10:13], v[80:83], v[116:119], v[10:13]
	v_mfma_f32_16x16x32_bf16 v[6:9], v[80:83], v[120:123], v[6:9]
	global_load_dwordx4 v[80:83], v[68:69], off offset:1088
	global_load_dwordx4 v[84:87], v[70:71], off offset:1152
	global_load_dwordx4 v[88:91], v[70:71], off offset:1168
	global_load_dwordx4 v[92:95], v[52:53], off offset:576
	global_load_dwordx4 v[96:99], v[54:55], off offset:576
	global_load_dwordx4 v[100:103], v[56:57], off offset:576
	global_load_dwordx4 v[104:107], v[58:59], off offset:576
	global_load_dwordx4 v[108:111], v[60:61], off offset:576
	global_load_dwordx4 v[112:115], v[62:63], off offset:576
	global_load_dwordx4 v[116:119], v[64:65], off offset:576
	global_load_dwordx4 v[120:123], v[66:67], off offset:576
	v_add_co_u32_e32 v68, vcc, 0x1d00, v68
	s_nop 1
	v_addc_co_u32_e32 v69, vcc, 0, v69, vcc
	s_waitcnt vmcnt(22)
; __device__ __forceinline__ float bf2f(u16 b) { return __uint_as_float(((unsigned)b) << 16); }
; __device__ void item_compress(const Params& p, int layer, int kv, int b, int g, int ct, unsigned char* smem) {
;     ...
;   for (int ii = 0; ii < 8; ++ii) {
;     const int i = wave * 8 + ii;
; #pragma unroll
;     for (int ks = 0; ks < 2; ++ks) {
;       uint4 raw = *(const uint4*)(src + (size_t)i * HS + ks * 32);
;       const float* pp = pe + i * 64 + ks * 32 + quad * 8;
;       float4 p0 = *(const float4*)pp, p1 = *(const float4*)(pp + 4);
;       bf16x8 a = pack8(bf2f((u16)(raw.x & 0xffff)) + p0.x, bf2f((u16)(raw.x >> 16)) + p0.y,
;                        bf2f((u16)(raw.y & 0xffff)) + p0.z, bf2f((u16)(raw.y >> 16)) + p0.w,
;                        bf2f((u16)(raw.z & 0xffff)) + p1.x, bf2f((u16)(raw.z >> 16)) + p1.y,
;                        bf2f((u16)(raw.w & 0xffff)) + p1.z, bf2f((u16)(raw.w >> 16)) + p1.w);
; #pragma unroll
;       for (int j = 0; j < 8; ++j) {
;         bf16x8 bfr = *(const bf16x8*)(wb + (size_t)(j * 16) * 2048 + i * 64 + ks * 32);
;         acc[j] = mfma16(a, bfr, acc[j]);
;       }
;     }
	v_lshlrev_b32_e32 v208, 16, v124
	v_and_b32_e32 v209, 0xffff0000, v124
	v_pk_add_f32 v[128:129], v[128:129], v[208:209]
	v_lshlrev_b32_e32 v208, 16, v125
	v_and_b32_e32 v209, 0xffff0000, v125
	v_pk_add_f32 v[130:131], v[130:131], v[208:209]
	v_lshlrev_b32_e32 v208, 16, v126
	v_and_b32_e32 v209, 0xffff0000, v126
	v_pk_add_f32 v[132:133], v[132:133], v[208:209]
	v_lshlrev_b32_e32 v208, 16, v127
	v_and_b32_e32 v209, 0xffff0000, v127
	v_pk_add_f32 v[134:135], v[134:135], v[208:209]
	v_cvt_pk_bf16_f32 v124, v128, v129
	v_cvt_pk_bf16_f32 v125, v130, v131
	v_cvt_pk_bf16_f32 v126, v132, v133
	v_cvt_pk_bf16_f32 v127, v134, v135
	s_nop 1
	v_mfma_f32_16x16x32_bf16 v[2:5], v[124:127], v[136:139], v[2:5]
	v_mfma_f32_16x16x32_bf16 v[30:33], v[124:127], v[140:143], v[30:33]
	v_mfma_f32_16x16x32_bf16 v[26:29], v[124:127], v[144:147], v[26:29]
	v_mfma_f32_16x16x32_bf16 v[22:25], v[124:127], v[148:151], v[22:25]
	v_mfma_f32_16x16x32_bf16 v[18:21], v[124:127], v[152:155], v[18:21]
	v_mfma_f32_16x16x32_bf16 v[14:17], v[124:127], v[156:159], v[14:17]
	v_mfma_f32_16x16x32_bf16 v[10:13], v[124:127], v[160:163], v[10:13]
	v_mfma_f32_16x16x32_bf16 v[6:9], v[124:127], v[164:167], v[6:9]
	global_load_dwordx4 v[124:127], v[68:69], off offset:1024
	global_load_dwordx4 v[128:131], v[70:71], off offset:1280
	global_load_dwordx4 v[132:135], v[70:71], off offset:1296
	global_load_dwordx4 v[136:139], v[52:53], off offset:640
	global_load_dwordx4 v[140:143], v[54:55], off offset:640
	global_load_dwordx4 v[144:147], v[56:57], off offset:640
	global_load_dwordx4 v[148:151], v[58:59], off offset:640
	global_load_dwordx4 v[152:155], v[60:61], off offset:640
	global_load_dwordx4 v[156:159], v[62:63], off offset:640
	global_load_dwordx4 v[160:163], v[64:65], off offset:640
	global_load_dwordx4 v[164:167], v[66:67], off offset:640
	s_waitcnt vmcnt(22)
	v_lshlrev_b32_e32 v208, 16, v168
	v_and_b32_e32 v209, 0xffff0000, v168
	v_pk_add_f32 v[172:173], v[172:173], v[208:209]
	v_lshlrev_b32_e32 v208, 16, v169
	v_and_b32_e32 v209, 0xffff0000, v169
	v_pk_add_f32 v[174:175], v[174:175], v[208:209]
	v_lshlrev_b32_e32 v208, 16, v170
	v_and_b32_e32 v209, 0xffff0000, v170
	v_pk_add_f32 v[176:177], v[176:177], v[208:209]
	v_lshlrev_b32_e32 v208, 16, v171
	v_and_b32_e32 v209, 0xffff0000, v171
	v_pk_add_f32 v[178:179], v[178:179], v[208:209]
	v_cvt_pk_bf16_f32 v168, v172, v173
	v_cvt_pk_bf16_f32 v169, v174, v175
	v_cvt_pk_bf16_f32 v170, v176, v177
	v_cvt_pk_bf16_f32 v171, v178, v179
	s_nop 1
	v_mfma_f32_16x16x32_bf16 v[2:5], v[168:171], v[180:183], v[2:5]
	v_mfma_f32_16x16x32_bf16 v[30:33], v[168:171], v[184:187], v[30:33]
	v_mfma_f32_16x16x32_bf16 v[26:29], v[168:171], v[188:191], v[26:29]
	v_mfma_f32_16x16x32_bf16 v[22:25], v[168:171], v[192:195], v[22:25]
	v_mfma_f32_16x16x32_bf16 v[18:21], v[168:171], v[196:199], v[18:21]
	v_mfma_f32_16x16x32_bf16 v[14:17], v[168:171], v[200:203], v[14:17]
	v_mfma_f32_16x16x32_bf16 v[10:13], v[168:171], v[204:207], v[10:13]
	v_mfma_f32_16x16x32_bf16 v[6:9], v[168:171], v[218:221], v[6:9]
	global_load_dwordx4 v[168:171], v[68:69], off offset:1088
	global_load_dwordx4 v[172:175], v[70:71], off offset:1408
	global_load_dwordx4 v[176:179], v[70:71], off offset:1424
	global_load_dwordx4 v[180:183], v[52:53], off offset:704
	global_load_dwordx4 v[184:187], v[54:55], off offset:704
	global_load_dwordx4 v[188:191], v[56:57], off offset:704
	global_load_dwordx4 v[192:195], v[58:59], off offset:704
	global_load_dwordx4 v[196:199], v[60:61], off offset:704
	global_load_dwordx4 v[200:203], v[62:63], off offset:704
	global_load_dwordx4 v[204:207], v[64:65], off offset:704
	global_load_dwordx4 v[218:221], v[66:67], off offset:704
	v_add_co_u32_e32 v68, vcc, 0x1d00, v68
	s_nop 1
	v_addc_co_u32_e32 v69, vcc, 0, v69, vcc
	s_waitcnt vmcnt(22)
	v_lshlrev_b32_e32 v208, 16, v80
	v_and_b32_e32 v209, 0xffff0000, v80
	v_pk_add_f32 v[84:85], v[84:85], v[208:209]
	v_lshlrev_b32_e32 v208, 16, v81
	v_and_b32_e32 v209, 0xffff0000, v81
	v_pk_add_f32 v[86:87], v[86:87], v[208:209]
	v_lshlrev_b32_e32 v208, 16, v82
	v_and_b32_e32 v209, 0xffff0000, v82
	v_pk_add_f32 v[88:89], v[88:89], v[208:209]
	v_lshlrev_b32_e32 v208, 16, v83
	v_and_b32_e32 v209, 0xffff0000, v83
	v_pk_add_f32 v[90:91], v[90:91], v[208:209]
	v_cvt_pk_bf16_f32 v80, v84, v85
	v_cvt_pk_bf16_f32 v81, v86, v87
	v_cvt_pk_bf16_f32 v82, v88, v89
	v_cvt_pk_bf16_f32 v83, v90, v91
	s_nop 1
	v_mfma_f32_16x16x32_bf16 v[2:5], v[80:83], v[92:95], v[2:5]
	v_mfma_f32_16x16x32_bf16 v[30:33], v[80:83], v[96:99], v[30:33]
	v_mfma_f32_16x16x32_bf16 v[26:29], v[80:83], v[100:103], v[26:29]
	v_mfma_f32_16x16x32_bf16 v[22:25], v[80:83], v[104:107], v[22:25]
	v_mfma_f32_16x16x32_bf16 v[18:21], v[80:83], v[108:111], v[18:21]
	v_mfma_f32_16x16x32_bf16 v[14:17], v[80:83], v[112:115], v[14:17]
	v_mfma_f32_16x16x32_bf16 v[10:13], v[80:83], v[116:119], v[10:13]
	v_mfma_f32_16x16x32_bf16 v[6:9], v[80:83], v[120:123], v[6:9]
	global_load_dwordx4 v[80:83], v[68:69], off offset:1024
	global_load_dwordx4 v[84:87], v[70:71], off offset:1536
	global_load_dwordx4 v[88:91], v[70:71], off offset:1552
	global_load_dwordx4 v[92:95], v[52:53], off offset:768
	global_load_dwordx4 v[96:99], v[54:55], off offset:768
	global_load_dwordx4 v[100:103], v[56:57], off offset:768
	global_load_dwordx4 v[104:107], v[58:59], off offset:768
	global_load_dwordx4 v[108:111], v[60:61], off offset:768
	global_load_dwordx4 v[112:115], v[62:63], off offset:768
	global_load_dwordx4 v[116:119], v[64:65], off offset:768
	global_load_dwordx4 v[120:123], v[66:67], off offset:768
	s_waitcnt vmcnt(22)
; __device__ __forceinline__ float bf2f(u16 b) { return __uint_as_float(((unsigned)b) << 16); }
; __device__ void item_compress(const Params& p, int layer, int kv, int b, int g, int ct, unsigned char* smem) {
;     ...
;   for (int ii = 0; ii < 8; ++ii) {
;     const int i = wave * 8 + ii;
; #pragma unroll
;     for (int ks = 0; ks < 2; ++ks) {
;       uint4 raw = *(const uint4*)(src + (size_t)i * HS + ks * 32);
;       const float* pp = pe + i * 64 + ks * 32 + quad * 8;
;       float4 p0 = *(const float4*)pp, p1 = *(const float4*)(pp + 4);
;       bf16x8 a = pack8(bf2f((u16)(raw.x & 0xffff)) + p0.x, bf2f((u16)(raw.x >> 16)) + p0.y,
;                        bf2f((u16)(raw.y & 0xffff)) + p0.z, bf2f((u16)(raw.y >> 16)) + p0.w,
;                        bf2f((u16)(raw.z & 0xffff)) + p1.x, bf2f((u16)(raw.z >> 16)) + p1.y,
;                        bf2f((u16)(raw.w & 0xffff)) + p1.z, bf2f((u16)(raw.w >> 16)) + p1.w);
; #pragma unroll
;       for (int j = 0; j < 8; ++j) {
;         bf16x8 bfr = *(const bf16x8*)(wb + (size_t)(j * 16) * 2048 + i * 64 + ks * 32);
;         acc[j] = mfma16(a, bfr, acc[j]);
;       }
;     }
	v_lshlrev_b32_e32 v208, 16, v124
	v_and_b32_e32 v209, 0xffff0000, v124
	v_pk_add_f32 v[128:129], v[128:129], v[208:209]
	v_lshlrev_b32_e32 v208, 16, v125
	v_and_b32_e32 v209, 0xffff0000, v125
	v_pk_add_f32 v[130:131], v[130:131], v[208:209]
	v_lshlrev_b32_e32 v208, 16, v126
	v_and_b32_e32 v209, 0xffff0000, v126
	v_pk_add_f32 v[132:133], v[132:133], v[208:209]
	v_lshlrev_b32_e32 v208, 16, v127
	v_and_b32_e32 v209, 0xffff0000, v127
	v_pk_add_f32 v[134:135], v[134:135], v[208:209]
	v_cvt_pk_bf16_f32 v124, v128, v129
	v_cvt_pk_bf16_f32 v125, v130, v131
	v_cvt_pk_bf16_f32 v126, v132, v133
	v_cvt_pk_bf16_f32 v127, v134, v135
	s_nop 1
	v_mfma_f32_16x16x32_bf16 v[2:5], v[124:127], v[136:139], v[2:5]
	v_mfma_f32_16x16x32_bf16 v[30:33], v[124:127], v[140:143], v[30:33]
	v_mfma_f32_16x16x32_bf16 v[26:29], v[124:127], v[144:147], v[26:29]
	v_mfma_f32_16x16x32_bf16 v[22:25], v[124:127], v[148:151], v[22:25]
	v_mfma_f32_16x16x32_bf16 v[18:21], v[124:127], v[152:155], v[18:21]
	v_mfma_f32_16x16x32_bf16 v[14:17], v[124:127], v[156:159], v[14:17]
	v_mfma_f32_16x16x32_bf16 v[10:13], v[124:127], v[160:163], v[10:13]
	v_mfma_f32_16x16x32_bf16 v[6:9], v[124:127], v[164:167], v[6:9]
	global_load_dwordx4 v[124:127], v[68:69], off offset:1088
	global_load_dwordx4 v[128:131], v[70:71], off offset:1664
	global_load_dwordx4 v[132:135], v[70:71], off offset:1680
	global_load_dwordx4 v[136:139], v[52:53], off offset:832
	global_load_dwordx4 v[140:143], v[54:55], off offset:832
	global_load_dwordx4 v[144:147], v[56:57], off offset:832
	global_load_dwordx4 v[148:151], v[58:59], off offset:832
	global_load_dwordx4 v[152:155], v[60:61], off offset:832
	global_load_dwordx4 v[156:159], v[62:63], off offset:832
	global_load_dwordx4 v[160:163], v[64:65], off offset:832
	global_load_dwordx4 v[164:167], v[66:67], off offset:832
	v_add_co_u32_e32 v68, vcc, 0x1d00, v68
	s_nop 1
	v_addc_co_u32_e32 v69, vcc, 0, v69, vcc
	s_waitcnt vmcnt(22)
	v_lshlrev_b32_e32 v208, 16, v168
	v_and_b32_e32 v209, 0xffff0000, v168
	v_pk_add_f32 v[172:173], v[172:173], v[208:209]
	v_lshlrev_b32_e32 v208, 16, v169
	v_and_b32_e32 v209, 0xffff0000, v169
	v_pk_add_f32 v[174:175], v[174:175], v[208:209]
	v_lshlrev_b32_e32 v208, 16, v170
	v_and_b32_e32 v209, 0xffff0000, v170
	v_pk_add_f32 v[176:177], v[176:177], v[208:209]
	v_lshlrev_b32_e32 v208, 16, v171
	v_and_b32_e32 v209, 0xffff0000, v171
	v_pk_add_f32 v[178:179], v[178:179], v[208:209]
	v_cvt_pk_bf16_f32 v168, v172, v173
	v_cvt_pk_bf16_f32 v169, v174, v175
	v_cvt_pk_bf16_f32 v170, v176, v177
	v_cvt_pk_bf16_f32 v171, v178, v179
	s_nop 1
	v_mfma_f32_16x16x32_bf16 v[2:5], v[168:171], v[180:183], v[2:5]
	v_mfma_f32_16x16x32_bf16 v[30:33], v[168:171], v[184:187], v[30:33]
	v_mfma_f32_16x16x32_bf16 v[26:29], v[168:171], v[188:191], v[26:29]
	v_mfma_f32_16x16x32_bf16 v[22:25], v[168:171], v[192:195], v[22:25]
	v_mfma_f32_16x16x32_bf16 v[18:21], v[168:171], v[196:199], v[18:21]
	v_mfma_f32_16x16x32_bf16 v[14:17], v[168:171], v[200:203], v[14:17]
	v_mfma_f32_16x16x32_bf16 v[10:13], v[168:171], v[204:207], v[10:13]
	v_mfma_f32_16x16x32_bf16 v[6:9], v[168:171], v[218:221], v[6:9]
	global_load_dwordx4 v[168:171], v[68:69], off offset:1024
	global_load_dwordx4 v[172:175], v[70:71], off offset:1792
	global_load_dwordx4 v[176:179], v[70:71], off offset:1808
	global_load_dwordx4 v[180:183], v[52:53], off offset:896
	global_load_dwordx4 v[184:187], v[54:55], off offset:896
	global_load_dwordx4 v[188:191], v[56:57], off offset:896
	global_load_dwordx4 v[192:195], v[58:59], off offset:896
	global_load_dwordx4 v[196:199], v[60:61], off offset:896
	global_load_dwordx4 v[200:203], v[62:63], off offset:896
	global_load_dwordx4 v[204:207], v[64:65], off offset:896
	global_load_dwordx4 v[218:221], v[66:67], off offset:896
	s_waitcnt vmcnt(22)
	v_lshlrev_b32_e32 v208, 16, v80
	v_and_b32_e32 v209, 0xffff0000, v80
	v_pk_add_f32 v[84:85], v[84:85], v[208:209]
	v_lshlrev_b32_e32 v208, 16, v81
	v_and_b32_e32 v209, 0xffff0000, v81
	v_pk_add_f32 v[86:87], v[86:87], v[208:209]
	v_lshlrev_b32_e32 v208, 16, v82
	v_and_b32_e32 v209, 0xffff0000, v82
	v_pk_add_f32 v[88:89], v[88:89], v[208:209]
	v_lshlrev_b32_e32 v208, 16, v83
	v_and_b32_e32 v209, 0xffff0000, v83
	v_pk_add_f32 v[90:91], v[90:91], v[208:209]
	v_cvt_pk_bf16_f32 v80, v84, v85
	v_cvt_pk_bf16_f32 v81, v86, v87
	v_cvt_pk_bf16_f32 v82, v88, v89
	v_cvt_pk_bf16_f32 v83, v90, v91
	s_nop 1
	v_mfma_f32_16x16x32_bf16 v[2:5], v[80:83], v[92:95], v[2:5]
	v_mfma_f32_16x16x32_bf16 v[30:33], v[80:83], v[96:99], v[30:33]
	v_mfma_f32_16x16x32_bf16 v[26:29], v[80:83], v[100:103], v[26:29]
	v_mfma_f32_16x16x32_bf16 v[22:25], v[80:83], v[104:107], v[22:25]
	v_mfma_f32_16x16x32_bf16 v[18:21], v[80:83], v[108:111], v[18:21]
	v_mfma_f32_16x16x32_bf16 v[14:17], v[80:83], v[112:115], v[14:17]
	v_mfma_f32_16x16x32_bf16 v[10:13], v[80:83], v[116:119], v[10:13]
	v_mfma_f32_16x16x32_bf16 v[6:9], v[80:83], v[120:123], v[6:9]
	global_load_dwordx4 v[80:83], v[68:69], off offset:1088
	global_load_dwordx4 v[84:87], v[70:71], off offset:1920
	global_load_dwordx4 v[88:91], v[70:71], off offset:1936
	global_load_dwordx4 v[92:95], v[52:53], off offset:960
	global_load_dwordx4 v[96:99], v[54:55], off offset:960
	global_load_dwordx4 v[100:103], v[56:57], off offset:960
	global_load_dwordx4 v[104:107], v[58:59], off offset:960
	global_load_dwordx4 v[108:111], v[60:61], off offset:960
	global_load_dwordx4 v[112:115], v[62:63], off offset:960
	global_load_dwordx4 v[116:119], v[64:65], off offset:960
	global_load_dwordx4 v[120:123], v[66:67], off offset:960
	s_waitcnt vmcnt(22)
; __device__ __forceinline__ float bf2f(u16 b) { return __uint_as_float(((unsigned)b) << 16); }
; __device__ void item_compress(const Params& p, int layer, int kv, int b, int g, int ct, unsigned char* smem) {
;     ...
;   for (int ii = 0; ii < 8; ++ii) {
;     const int i = wave * 8 + ii;
; #pragma unroll
;     for (int ks = 0; ks < 2; ++ks) {
;       uint4 raw = *(const uint4*)(src + (size_t)i * HS + ks * 32);
;       const float* pp = pe + i * 64 + ks * 32 + quad * 8;
;       float4 p0 = *(const float4*)pp, p1 = *(const float4*)(pp + 4);
;       bf16x8 a = pack8(bf2f((u16)(raw.x & 0xffff)) + p0.x, bf2f((u16)(raw.x >> 16)) + p0.y,
;                        bf2f((u16)(raw.y & 0xffff)) + p0.z, bf2f((u16)(raw.y >> 16)) + p0.w,
;                        bf2f((u16)(raw.z & 0xffff)) + p1.x, bf2f((u16)(raw.z >> 16)) + p1.y,
;                        bf2f((u16)(raw.w & 0xffff)) + p1.z, bf2f((u16)(raw.w >> 16)) + p1.w);
; #pragma unroll
;       for (int j = 0; j < 8; ++j) {
;         bf16x8 bfr = *(const bf16x8*)(wb + (size_t)(j * 16) * 2048 + i * 64 + ks * 32);
;         acc[j] = mfma16(a, bfr, acc[j]);
;       }
;     }
;   }
;   __syncthreads();
; #pragma unroll
;   for (int j = 0; j < 8; ++j)
; #pragma unroll
;     for (int r = 0; r < 4; ++r) sP[(wave * 16 + quad * 4 + r) * 132 + j * 16 + l15] = acc[j][r];
;   __syncthreads();
	v_lshlrev_b32_e32 v208, 16, v124
	v_and_b32_e32 v209, 0xffff0000, v124
	v_pk_add_f32 v[128:129], v[128:129], v[208:209]
	v_lshlrev_b32_e32 v208, 16, v125
	v_and_b32_e32 v209, 0xffff0000, v125
	v_pk_add_f32 v[130:131], v[130:131], v[208:209]
	v_lshlrev_b32_e32 v208, 16, v126
	v_and_b32_e32 v209, 0xffff0000, v126
	v_pk_add_f32 v[132:133], v[132:133], v[208:209]
	v_lshlrev_b32_e32 v208, 16, v127
	v_and_b32_e32 v209, 0xffff0000, v127
	v_pk_add_f32 v[134:135], v[134:135], v[208:209]
	v_cvt_pk_bf16_f32 v124, v128, v129
	v_cvt_pk_bf16_f32 v125, v130, v131
	v_cvt_pk_bf16_f32 v126, v132, v133
	v_cvt_pk_bf16_f32 v127, v134, v135
	s_nop 1
	v_mfma_f32_16x16x32_bf16 v[2:5], v[124:127], v[136:139], v[2:5]
	v_mfma_f32_16x16x32_bf16 v[30:33], v[124:127], v[140:143], v[30:33]
	v_mfma_f32_16x16x32_bf16 v[26:29], v[124:127], v[144:147], v[26:29]
	v_mfma_f32_16x16x32_bf16 v[22:25], v[124:127], v[148:151], v[22:25]
	v_mfma_f32_16x16x32_bf16 v[18:21], v[124:127], v[152:155], v[18:21]
	v_mfma_f32_16x16x32_bf16 v[14:17], v[124:127], v[156:159], v[14:17]
	v_mfma_f32_16x16x32_bf16 v[10:13], v[124:127], v[160:163], v[10:13]
	v_mfma_f32_16x16x32_bf16 v[6:9], v[124:127], v[164:167], v[6:9]
	s_waitcnt vmcnt(11)
	v_lshlrev_b32_e32 v208, 16, v168
	v_and_b32_e32 v209, 0xffff0000, v168
	v_pk_add_f32 v[172:173], v[172:173], v[208:209]
	v_lshlrev_b32_e32 v208, 16, v169
	v_and_b32_e32 v209, 0xffff0000, v169
	v_pk_add_f32 v[174:175], v[174:175], v[208:209]
	v_lshlrev_b32_e32 v208, 16, v170
	v_and_b32_e32 v209, 0xffff0000, v170
	v_pk_add_f32 v[176:177], v[176:177], v[208:209]
	v_lshlrev_b32_e32 v208, 16, v171
	v_and_b32_e32 v209, 0xffff0000, v171
	v_pk_add_f32 v[178:179], v[178:179], v[208:209]
	v_cvt_pk_bf16_f32 v168, v172, v173
	v_cvt_pk_bf16_f32 v169, v174, v175
	v_cvt_pk_bf16_f32 v170, v176, v177
	v_cvt_pk_bf16_f32 v171, v178, v179
	s_nop 1
	v_mfma_f32_16x16x32_bf16 v[2:5], v[168:171], v[180:183], v[2:5]
	v_mfma_f32_16x16x32_bf16 v[30:33], v[168:171], v[184:187], v[30:33]
	v_mfma_f32_16x16x32_bf16 v[26:29], v[168:171], v[188:191], v[26:29]
	v_mfma_f32_16x16x32_bf16 v[22:25], v[168:171], v[192:195], v[22:25]
	v_mfma_f32_16x16x32_bf16 v[18:21], v[168:171], v[196:199], v[18:21]
	v_mfma_f32_16x16x32_bf16 v[14:17], v[168:171], v[200:203], v[14:17]
	v_mfma_f32_16x16x32_bf16 v[10:13], v[168:171], v[204:207], v[10:13]
	v_mfma_f32_16x16x32_bf16 v[6:9], v[168:171], v[218:221], v[6:9]
	s_waitcnt vmcnt(0)
	v_lshlrev_b32_e32 v208, 16, v80
	v_and_b32_e32 v209, 0xffff0000, v80
	v_pk_add_f32 v[84:85], v[84:85], v[208:209]
	v_lshlrev_b32_e32 v208, 16, v81
	v_and_b32_e32 v209, 0xffff0000, v81
	v_pk_add_f32 v[86:87], v[86:87], v[208:209]
	v_lshlrev_b32_e32 v208, 16, v82
	v_and_b32_e32 v209, 0xffff0000, v82
	v_pk_add_f32 v[88:89], v[88:89], v[208:209]
	v_lshlrev_b32_e32 v208, 16, v83
	v_and_b32_e32 v209, 0xffff0000, v83
	v_pk_add_f32 v[90:91], v[90:91], v[208:209]
	v_cvt_pk_bf16_f32 v80, v84, v85
	v_cvt_pk_bf16_f32 v81, v86, v87
	v_cvt_pk_bf16_f32 v82, v88, v89
	v_cvt_pk_bf16_f32 v83, v90, v91
	s_nop 1
	v_mfma_f32_16x16x32_bf16 v[2:5], v[80:83], v[92:95], v[2:5]
	v_mfma_f32_16x16x32_bf16 v[30:33], v[80:83], v[96:99], v[30:33]
	v_mfma_f32_16x16x32_bf16 v[26:29], v[80:83], v[100:103], v[26:29]
	v_mfma_f32_16x16x32_bf16 v[22:25], v[80:83], v[104:107], v[22:25]
	v_mfma_f32_16x16x32_bf16 v[18:21], v[80:83], v[108:111], v[18:21]
	v_mfma_f32_16x16x32_bf16 v[14:17], v[80:83], v[112:115], v[14:17]
	v_mfma_f32_16x16x32_bf16 v[10:13], v[80:83], v[116:119], v[10:13]
	v_mfma_f32_16x16x32_bf16 v[6:9], v[80:83], v[120:123], v[6:9]
	v_and_b32_e32 v34, 3, v74
	v_lshlrev_b32_e32 v35, 4, v75
	v_lshlrev_b32_e32 v36, 2, v34
	v_or_b32_e32 v0, v36, v35
	s_movk_i32 s39, 0x210
	v_mul_lo_u32 v0, v0, s39
	v_lshl_or_b32 v0, v72, 2, v0
	s_waitcnt lgkmcnt(0)
	s_barrier
	ds_write2_b32 v0, v2, v30 offset1:16
	ds_write2_b32 v0, v3, v31 offset0:132 offset1:148
	v_add_u32_e32 v2, 0x400, v0
	ds_write2_b32 v2, v4, v32 offset0:8 offset1:24
	ds_write2_b32 v2, v5, v33 offset0:140 offset1:156
	ds_write2_b32 v0, v26, v22 offset0:32 offset1:48
	ds_write2_b32 v0, v27, v23 offset0:164 offset1:180
	ds_write2_b32 v2, v28, v24 offset0:40 offset1:56
	ds_write2_b32 v2, v29, v25 offset0:172 offset1:188
	ds_write2_b32 v0, v18, v14 offset0:64 offset1:80
	ds_write2_b32 v0, v19, v15 offset0:196 offset1:212
	ds_write2_b32 v2, v20, v16 offset0:72 offset1:88
	ds_write2_b32 v2, v21, v17 offset0:204 offset1:220
	ds_write2_b32 v0, v10, v6 offset0:96 offset1:112
	ds_write2_b32 v0, v11, v7 offset0:228 offset1:244
	ds_write2_b32 v2, v12, v8 offset0:104 offset1:120
	ds_write2_b32 v2, v13, v9 offset0:236 offset1:252
	v_and_b32_e32 v6, 0x7f, v73
	s_and_b32 s38, s40, 1
	v_lshlrev_b32_e32 v0, 2, v6
	v_ashrrev_i32_e32 v8, 7, v73
	s_and_b64 s[30:31], s[30:31], exec
	v_mad_u64_u32 v[2:3], s[30:31], v8, s39, v[0:1]
	s_waitcnt lgkmcnt(0)
	s_barrier
; __device__ __forceinline__ float silu_f(float x) { return x * __builtin_amdgcn_rcpf(1.f + __expf(-x)); }
; __device__ void item_compress(const Params& p, int layer, int kv, int b, int g, int ct, unsigned char* smem) {
;     ...
; #pragma unroll
;   for (int e = 0; e < 8; ++e) {
;     int idx = e * 256 + tid;
;     int row = idx >> 7, cc = idx & 127;
;     float v = ((sP[row * 132 + cc] + sP[(16 + row) * 132 + cc]) + sP[(32 + row) * 132 + cc]) + sP[(48 + row) * 132 + cc];
;     v = silu_f(v);
;     sH[row * 136 + cc] = (u16)(pack2(v, 0.f) & 0xffff);
;   }
;   __syncthreads();
;   f32x4 a2 = f32x4{0.f, 0.f, 0.f, 0.f};
; #pragma unroll
;   for (int ks = 0; ks < 4; ++ks) {
;     bf16x8 a = *(const bf16x8*)(sH + l15 * 136 + ks * 32 + quad * 8);
;     bf16x8 bb = *(const bf16x8*)(w2t + (size_t)(wave * 16 + l15) * 128 + ks * 32 + quad * 8);
;     a2 = mfma16(a, bb, a2);
;   }
;   const int d = wave * 16 + l15;
;   const int cc = c0 + quad * 4;
;   float v0 = a2[0], v1 = a2[1], v2 = a2[2], v3 = (cc + 3 < 127) ? a2[3] : 0.f;
;   if (kv == 0) {
;     u16* dst = P_KCMP + ((size_t)(b * 2 + g) * 128 + cc) * 64 + d;
;     dst[0] = (u16)(pack2(v0, 0.f) & 0xffff);
;     dst[64] = (u16)(pack2(v1, 0.f) & 0xffff);
;     dst[128] = (u16)(pack2(v2, 0.f) & 0xffff);
;     dst[192] = (u16)(pack2(v3, 0.f) & 0xffff);
;   } else {
;     uint2 o; o.x = pack2(v0, v1); o.y = pack2(v2, v3);
;     *(uint2*)(P_VCMP_T + ((size_t)(b * 2 + g) * 64 + d) * 128 + cc) = o;
;   }
; }
	ds_read2st64_b32 v[4:5], v2 offset1:33
	ds_read2st64_b32 v[2:3], v2 offset0:66 offset1:99
	v_lshlrev_b32_e32 v6, 1, v6
	s_mov_b32 s30, 0x2904400
	s_cselect_b32 s30, s30, 0x2914400
	s_waitcnt lgkmcnt(1)
	v_add_f32_e32 v4, v4, v5
	s_waitcnt lgkmcnt(0)
	v_add_f32_e32 v2, v4, v2
	v_add_f32_e32 v7, v2, v3
	v_mul_f32_e32 v2, 0xbfb8aa3b, v7
	v_exp_f32_e32 v9, v2
	v_add_u32_e32 v2, 0x100, v73
	v_ashrrev_i32_e32 v10, 7, v2
	v_mad_u64_u32 v[2:3], s[40:41], v10, s39, v[0:1]
	ds_read2st64_b32 v[4:5], v2 offset1:33
	ds_read2st64_b32 v[2:3], v2 offset0:66 offset1:99
	v_add_f32_e32 v9, 1.0, v9
	v_rcp_f32_e32 v9, v9
	s_add_u32 s30, s9, s30
	s_waitcnt lgkmcnt(1)
	v_add_f32_e32 v4, v4, v5
	s_waitcnt lgkmcnt(0)
	v_add_f32_e32 v2, v4, v2
	v_add_f32_e32 v3, v2, v3
	v_mul_f32_e32 v2, 0xbfb8aa3b, v3
	v_exp_f32_e32 v4, v2
	v_mul_f32_e32 v5, v7, v9
	v_cvt_pk_bf16_f32 v11, v5, s0
	v_sub_u32_e32 v2, v0, v6
	v_add_f32_e32 v4, 1.0, v4
	v_rcp_f32_e32 v12, v4
	v_add_u32_e32 v4, 0x200, v73
	v_ashrrev_i32_e32 v13, 7, v4
	v_mad_u64_u32 v[4:5], s[40:41], v13, s39, v[0:1]
	ds_read2st64_b32 v[6:7], v4 offset1:33
	ds_read2st64_b32 v[4:5], v4 offset0:66 offset1:99
	v_mad_u64_u32 v[8:9], s[40:41], v8, s5, v[2:3]
	ds_write_b16 v8, v11 offset:33792
	s_waitcnt lgkmcnt(2)
	v_add_f32_e32 v6, v6, v7
	s_waitcnt lgkmcnt(1)
	v_add_f32_e32 v4, v6, v4
	v_add_f32_e32 v11, v4, v5
	v_mul_f32_e32 v4, 0xbfb8aa3b, v11
	v_exp_f32_e32 v6, v4
	v_mul_f32_e32 v3, v3, v12
	v_cvt_pk_bf16_f32 v3, v3, s0
	v_mad_u64_u32 v[4:5], s[40:41], v10, s5, v[2:3]
	v_add_f32_e32 v5, 1.0, v6
	v_add_u32_e32 v6, 0x300, v73
	v_ashrrev_i32_e32 v10, 7, v6
	v_mad_u64_u32 v[6:7], s[40:41], v10, s39, v[0:1]
	ds_read2st64_b32 v[8:9], v6 offset1:33
	ds_read2st64_b32 v[6:7], v6 offset0:66 offset1:99
	v_rcp_f32_e32 v5, v5
	ds_write_b16 v4, v3 offset:33792
	s_addc_u32 s31, s12, 0
	s_waitcnt lgkmcnt(2)
	v_add_f32_e32 v4, v8, v9
	s_waitcnt lgkmcnt(1)
	v_add_f32_e32 v4, v4, v6
	v_mul_f32_e32 v3, v11, v5
	v_add_f32_e32 v11, v4, v7
	v_mul_f32_e32 v4, 0xbfb8aa3b, v11
	v_exp_f32_e32 v12, v4
	v_add_u32_e32 v4, 0x400, v73
	v_ashrrev_i32_e32 v14, 7, v4
	v_mad_u64_u32 v[4:5], s[40:41], v14, s39, v[0:1]
	ds_read2st64_b32 v[6:7], v4 offset1:33
	ds_read2st64_b32 v[4:5], v4 offset0:66 offset1:99
	v_cvt_pk_bf16_f32 v3, v3, s0
	v_mad_u64_u32 v[8:9], s[40:41], v13, s5, v[2:3]
	s_waitcnt lgkmcnt(1)
	v_add_f32_e32 v6, v6, v7
	s_waitcnt lgkmcnt(0)
	v_add_f32_e32 v4, v6, v4
	v_add_f32_e32 v9, 1.0, v12
	v_add_f32_e32 v12, v4, v5
	v_mul_f32_e32 v4, 0xbfb8aa3b, v12
	v_exp_f32_e32 v4, v4
	v_rcp_f32_e32 v9, v9
	ds_write_b16 v8, v3 offset:33792
	v_add_f32_e32 v4, 1.0, v4
	v_mul_f32_e32 v3, v11, v9
	v_rcp_f32_e32 v11, v4
	v_add_u32_e32 v4, 0x500, v73
	v_ashrrev_i32_e32 v13, 7, v4
	v_mad_u64_u32 v[4:5], s[40:41], v13, s39, v[0:1]
	ds_read2st64_b32 v[6:7], v4 offset1:33
	ds_read2st64_b32 v[4:5], v4 offset0:66 offset1:99
	v_cvt_pk_bf16_f32 v3, v3, s0
	v_mad_u64_u32 v[8:9], s[40:41], v10, s5, v[2:3]
	s_waitcnt lgkmcnt(1)
	v_add_f32_e32 v6, v6, v7
	s_waitcnt lgkmcnt(0)
	v_add_f32_e32 v4, v6, v4
	v_add_f32_e32 v10, v4, v5
	v_mul_f32_e32 v4, 0xbfb8aa3b, v10
	v_exp_f32_e32 v6, v4
	ds_write_b16 v8, v3 offset:33792
	v_mul_f32_e32 v3, v12, v11
	v_cvt_pk_bf16_f32 v3, v3, s0
	v_mad_u64_u32 v[4:5], s[40:41], v14, s5, v[2:3]
	v_add_f32_e32 v5, 1.0, v6
	v_add_u32_e32 v6, 0x600, v73
	v_ashrrev_i32_e32 v11, 7, v6
	v_mad_u64_u32 v[6:7], s[40:41], v11, s39, v[0:1]
	ds_read2st64_b32 v[8:9], v6 offset1:33
	ds_read2st64_b32 v[6:7], v6 offset0:66 offset1:99
	v_rcp_f32_e32 v5, v5
	ds_write_b16 v4, v3 offset:33792
	s_waitcnt lgkmcnt(2)
	v_add_f32_e32 v4, v8, v9
	s_waitcnt lgkmcnt(1)
	v_add_f32_e32 v4, v4, v6
	v_mul_f32_e32 v3, v10, v5
	v_add_f32_e32 v10, v4, v7
	v_mul_f32_e32 v4, 0xbfb8aa3b, v10
	v_exp_f32_e32 v12, v4
	v_add_u32_e32 v4, 0x700, v73
	v_ashrrev_i32_e32 v14, 7, v4
	v_mad_u64_u32 v[4:5], s[40:41], v14, s39, v[0:1]
	ds_read2st64_b32 v[6:7], v4 offset1:33
	ds_read2st64_b32 v[4:5], v4 offset0:66 offset1:99
	v_cvt_pk_bf16_f32 v3, v3, s0
	v_mad_u64_u32 v[8:9], s[40:41], v13, s5, v[2:3]
	s_waitcnt lgkmcnt(1)
	v_add_f32_e32 v6, v6, v7
	s_waitcnt lgkmcnt(0)
	v_add_f32_e32 v4, v6, v4
	v_add_f32_e32 v6, v4, v5
	v_mul_f32_e32 v4, 0xbfb8aa3b, v6
	v_exp_f32_e32 v4, v4
	v_add_f32_e32 v0, 1.0, v12
	v_rcp_f32_e32 v0, v0
	ds_write_b16 v8, v3 offset:33792
	v_add_f32_e32 v3, 1.0, v4
	v_rcp_f32_e32 v3, v3
	v_mul_f32_e32 v0, v10, v0
	v_cvt_pk_bf16_f32 v0, v0, s0
	v_mad_u64_u32 v[4:5], s[40:41], v11, s5, v[2:3]
	ds_write_b16 v4, v0 offset:33792
	v_mul_f32_e32 v0, v6, v3
	v_or_b32_e32 v6, v35, v72
	v_cvt_pk_bf16_f32 v0, v0, s0
	v_mad_u64_u32 v[2:3], s[40:41], v14, s5, v[2:3]
	v_ashrrev_i32_e32 v7, 31, v6
	ds_write_b16 v2, v0 offset:33792
	v_lshlrev_b64 v[2:3], 8, v[6:7]
	v_lshlrev_b32_e32 v0, 4, v34
	v_lshl_add_u64 v[2:3], s[30:31], 0, v[2:3]
	v_lshl_add_u64 v[16:17], v[2:3], 0, v[0:1]
	s_waitcnt lgkmcnt(0)
	s_barrier
	global_load_dwordx4 v[2:5], v[16:17], off
	global_load_dwordx4 v[8:11], v[16:17], off offset:64
	global_load_dwordx4 v[12:15], v[16:17], off offset:128
	s_nop 0
	global_load_dwordx4 v[16:19], v[16:17], off offset:192
	v_mad_u32_u24 v0, v72, s5, v0
	ds_read_b128 v[20:23], v0 offset:33792
	ds_read_b128 v[24:27], v0 offset:33856
	s_movk_i32 s30, 0x7c
	s_waitcnt vmcnt(3) lgkmcnt(1)
	v_mfma_f32_16x16x32_bf16 v[2:5], v[20:23], v[2:5], 0
	ds_read_b128 v[20:23], v0 offset:33920
	s_waitcnt vmcnt(2) lgkmcnt(1)
	v_mfma_f32_16x16x32_bf16 v[2:5], v[24:27], v[8:11], v[2:5]
	ds_read_b128 v[8:11], v0 offset:33984
	s_waitcnt vmcnt(1) lgkmcnt(1)
	v_mfma_f32_16x16x32_bf16 v[2:5], v[20:23], v[12:15], v[2:5]
	s_waitcnt vmcnt(0) lgkmcnt(0)
	v_mfma_f32_16x16x32_bf16 v[2:5], v[8:11], v[16:19], v[2:5]
	v_or_b32_e32 v11, s35, v36
	v_cmp_ne_u32_e32 vcc, s30, v11
	s_mov_b64 s[30:31], -1
	s_nop 4
	v_cndmask_b32_e32 v10, 0, v5, vcc
	s_and_b64 vcc, exec, s[18:19]
	v_cvt_pk_bf16_f32 v8, v2, v3
	s_cbranch_vccnz .LBB0_236
	s_andn2_b64 vcc, exec, s[30:31]
	s_cbranch_vccnz .LBB0_231
	s_branch .LBB0_237
